# GEMM main-loop heads aligned to 64-byte instruction-cache lines
# speedup vs baseline: 1.0113x; 1.0113x over previous
.LBB0_233:
	s_ashr_i32 s15, s14, 31
	s_lshl_b64 s[16:17], s[14:15], 19
	s_add_u32 s16, s26, s16
	s_addc_u32 s17, s27, s17
	s_and_b64 s[18:19], s[4:5], exec
	s_cselect_b32 s15, s17, s21
	s_cselect_b32 s42, s16, s20
	s_ashr_i32 s13, s12, 31
	s_lshl_b64 s[18:19], s[12:13], 19
	s_add_u32 s18, s28, s18
	s_addc_u32 s19, s29, s19
	s_and_b64 s[24:25], s[4:5], exec
	s_cselect_b32 s13, s19, s23
	s_cselect_b32 s43, s18, s22
	s_add_u32 s20, s20, 0x40080
	s_addc_u32 s21, s21, 0
	s_add_u32 s44, s22, 0x100
	v_mov_b32_e32 v2, 0
	s_addc_u32 s45, s23, 0
	s_mov_b32 s46, -2
	v_mov_b32_e32 v3, v2
	v_mov_b32_e32 v4, v2
	v_mov_b32_e32 v5, v2
	v_mov_b32_e32 v6, v2
	v_mov_b32_e32 v7, v2
	v_mov_b32_e32 v8, v2
	v_mov_b32_e32 v9, v2
	v_mov_b32_e32 v18, v2
	v_mov_b32_e32 v19, v2
	v_mov_b32_e32 v20, v2
	v_mov_b32_e32 v21, v2
	v_mov_b32_e32 v22, v2
	v_mov_b32_e32 v23, v2
	v_mov_b32_e32 v24, v2
	v_mov_b32_e32 v25, v2
	v_mov_b32_e32 v34, v2
	v_mov_b32_e32 v35, v2
	v_mov_b32_e32 v36, v2
	v_mov_b32_e32 v37, v2
	v_mov_b32_e32 v38, v2
	v_mov_b32_e32 v39, v2
	v_mov_b32_e32 v40, v2
	v_mov_b32_e32 v41, v2
	v_mov_b32_e32 v50, v2
	v_mov_b32_e32 v51, v2
	v_mov_b32_e32 v52, v2
	v_mov_b32_e32 v53, v2
	v_mov_b32_e32 v54, v2
	v_mov_b32_e32 v55, v2
	v_mov_b32_e32 v56, v2
	v_mov_b32_e32 v57, v2
	v_mov_b32_e32 v10, v2
	v_mov_b32_e32 v11, v2
	v_mov_b32_e32 v12, v2
	v_mov_b32_e32 v13, v2
	v_mov_b32_e32 v14, v2
	v_mov_b32_e32 v15, v2
	v_mov_b32_e32 v16, v2
	v_mov_b32_e32 v17, v2
	v_mov_b32_e32 v26, v2
	v_mov_b32_e32 v27, v2
	v_mov_b32_e32 v28, v2
	v_mov_b32_e32 v29, v2
	v_mov_b32_e32 v30, v2
	v_mov_b32_e32 v31, v2
	v_mov_b32_e32 v32, v2
	v_mov_b32_e32 v33, v2
	v_mov_b32_e32 v42, v2
	v_mov_b32_e32 v43, v2
	v_mov_b32_e32 v44, v2
	v_mov_b32_e32 v45, v2
	v_mov_b32_e32 v46, v2
	v_mov_b32_e32 v47, v2
	v_mov_b32_e32 v48, v2
	v_mov_b32_e32 v49, v2
	v_mov_b32_e32 v58, v2
	v_mov_b32_e32 v59, v2
	v_mov_b32_e32 v60, v2
	v_mov_b32_e32 v61, v2
	v_mov_b32_e32 v62, v2
	v_mov_b32_e32 v63, v2
	v_mov_b32_e32 v64, v2
	v_mov_b32_e32 v65, v2
	v_mov_b32_e32 v66, v2
	v_mov_b32_e32 v67, v2
	v_mov_b32_e32 v68, v2
	v_mov_b32_e32 v69, v2
	v_mov_b32_e32 v70, v2
	v_mov_b32_e32 v71, v2
	v_mov_b32_e32 v72, v2
	v_mov_b32_e32 v73, v2
	v_mov_b32_e32 v82, v2
	v_mov_b32_e32 v83, v2
	v_mov_b32_e32 v84, v2
	v_mov_b32_e32 v85, v2
	v_mov_b32_e32 v86, v2
	v_mov_b32_e32 v87, v2
	v_mov_b32_e32 v88, v2
	v_mov_b32_e32 v89, v2
	v_mov_b32_e32 v98, v2
	v_mov_b32_e32 v99, v2
	v_mov_b32_e32 v100, v2
	v_mov_b32_e32 v101, v2
	v_mov_b32_e32 v102, v2
	v_mov_b32_e32 v103, v2
	v_mov_b32_e32 v104, v2
	v_mov_b32_e32 v105, v2
	v_mov_b32_e32 v114, v2
	v_mov_b32_e32 v115, v2
	v_mov_b32_e32 v116, v2
	v_mov_b32_e32 v117, v2
	v_mov_b32_e32 v118, v2
	v_mov_b32_e32 v119, v2
	v_mov_b32_e32 v120, v2
	v_mov_b32_e32 v121, v2
	v_mov_b32_e32 v74, v2
	v_mov_b32_e32 v75, v2
	v_mov_b32_e32 v76, v2
	v_mov_b32_e32 v77, v2
	v_mov_b32_e32 v78, v2
	v_mov_b32_e32 v79, v2
	v_mov_b32_e32 v80, v2
	v_mov_b32_e32 v81, v2
	v_mov_b32_e32 v90, v2
	v_mov_b32_e32 v91, v2
	v_mov_b32_e32 v92, v2
	v_mov_b32_e32 v93, v2
	v_mov_b32_e32 v94, v2
	v_mov_b32_e32 v95, v2
	v_mov_b32_e32 v96, v2
	v_mov_b32_e32 v97, v2
	v_mov_b32_e32 v106, v2
	v_mov_b32_e32 v107, v2
	v_mov_b32_e32 v108, v2
	v_mov_b32_e32 v109, v2
	v_mov_b32_e32 v110, v2
	v_mov_b32_e32 v111, v2
	v_mov_b32_e32 v112, v2
	v_mov_b32_e32 v113, v2
	v_mov_b32_e32 v122, v2
	v_mov_b32_e32 v123, v2
	v_mov_b32_e32 v124, v2
	v_mov_b32_e32 v125, v2
	v_mov_b32_e32 v126, v2
	v_mov_b32_e32 v127, v2
	v_mov_b32_e32 v128, v2
	v_mov_b32_e32 v129, v2
	s_waitcnt vmcnt(0)
	.p2align 6

.LBB0_309:
	s_add_u32 s47, s22, 0x100
	v_mov_b32_e32 v2, 0
	s_addc_u32 s48, s23, 0
	s_mov_b32 s49, -2
	s_waitcnt lgkmcnt(0)
	v_mov_b32_e32 v3, v2
	v_mov_b32_e32 v4, v2
	v_mov_b32_e32 v5, v2
	v_mov_b32_e32 v6, v2
	v_mov_b32_e32 v7, v2
	v_mov_b32_e32 v8, v2
	v_mov_b32_e32 v9, v2
	v_mov_b32_e32 v18, v2
	v_mov_b32_e32 v19, v2
	v_mov_b32_e32 v20, v2
	v_mov_b32_e32 v21, v2
	v_mov_b32_e32 v22, v2
	v_mov_b32_e32 v23, v2
	v_mov_b32_e32 v24, v2
	v_mov_b32_e32 v25, v2
	v_mov_b32_e32 v34, v2
	v_mov_b32_e32 v35, v2
	v_mov_b32_e32 v36, v2
	v_mov_b32_e32 v37, v2
	v_mov_b32_e32 v38, v2
	v_mov_b32_e32 v39, v2
	v_mov_b32_e32 v40, v2
	v_mov_b32_e32 v41, v2
	v_mov_b32_e32 v50, v2
	v_mov_b32_e32 v51, v2
	v_mov_b32_e32 v52, v2
	v_mov_b32_e32 v53, v2
	v_mov_b32_e32 v54, v2
	v_mov_b32_e32 v55, v2
	v_mov_b32_e32 v56, v2
	v_mov_b32_e32 v57, v2
	v_mov_b32_e32 v10, v2
	v_mov_b32_e32 v11, v2
	v_mov_b32_e32 v12, v2
	v_mov_b32_e32 v13, v2
	v_mov_b32_e32 v14, v2
	v_mov_b32_e32 v15, v2
	v_mov_b32_e32 v16, v2
	v_mov_b32_e32 v17, v2
	v_mov_b32_e32 v26, v2
	v_mov_b32_e32 v27, v2
	v_mov_b32_e32 v28, v2
	v_mov_b32_e32 v29, v2
	v_mov_b32_e32 v30, v2
	v_mov_b32_e32 v31, v2
	v_mov_b32_e32 v32, v2
	v_mov_b32_e32 v33, v2
	v_mov_b32_e32 v42, v2
	v_mov_b32_e32 v43, v2
	v_mov_b32_e32 v44, v2
	v_mov_b32_e32 v45, v2
	v_mov_b32_e32 v46, v2
	v_mov_b32_e32 v47, v2
	v_mov_b32_e32 v48, v2
	v_mov_b32_e32 v49, v2
	v_mov_b32_e32 v58, v2
	v_mov_b32_e32 v59, v2
	v_mov_b32_e32 v60, v2
	v_mov_b32_e32 v61, v2
	v_mov_b32_e32 v62, v2
	v_mov_b32_e32 v63, v2
	v_mov_b32_e32 v64, v2
	v_mov_b32_e32 v65, v2
	v_mov_b32_e32 v66, v2
	v_mov_b32_e32 v67, v2
	v_mov_b32_e32 v68, v2
	v_mov_b32_e32 v69, v2
	v_mov_b32_e32 v70, v2
	v_mov_b32_e32 v71, v2
	v_mov_b32_e32 v72, v2
	v_mov_b32_e32 v73, v2
	v_mov_b32_e32 v82, v2
	v_mov_b32_e32 v83, v2
	v_mov_b32_e32 v84, v2
	v_mov_b32_e32 v85, v2
	v_mov_b32_e32 v86, v2
	v_mov_b32_e32 v87, v2
	v_mov_b32_e32 v88, v2
	v_mov_b32_e32 v89, v2
	v_mov_b32_e32 v98, v2
	v_mov_b32_e32 v99, v2
	v_mov_b32_e32 v100, v2
	v_mov_b32_e32 v101, v2
	v_mov_b32_e32 v102, v2
	v_mov_b32_e32 v103, v2
	v_mov_b32_e32 v104, v2
	v_mov_b32_e32 v105, v2
	v_mov_b32_e32 v114, v2
	v_mov_b32_e32 v115, v2
	v_mov_b32_e32 v116, v2
	v_mov_b32_e32 v117, v2
	v_mov_b32_e32 v118, v2
	v_mov_b32_e32 v119, v2
	v_mov_b32_e32 v120, v2
	v_mov_b32_e32 v121, v2
	v_mov_b32_e32 v74, v2
	v_mov_b32_e32 v75, v2
	v_mov_b32_e32 v76, v2
	v_mov_b32_e32 v77, v2
	v_mov_b32_e32 v78, v2
	v_mov_b32_e32 v79, v2
	v_mov_b32_e32 v80, v2
	v_mov_b32_e32 v81, v2
	v_mov_b32_e32 v90, v2
	v_mov_b32_e32 v91, v2
	v_mov_b32_e32 v92, v2
	v_mov_b32_e32 v93, v2
	v_mov_b32_e32 v94, v2
	v_mov_b32_e32 v95, v2
	v_mov_b32_e32 v96, v2
	v_mov_b32_e32 v97, v2
	v_mov_b32_e32 v106, v2
	v_mov_b32_e32 v107, v2
	v_mov_b32_e32 v108, v2
	v_mov_b32_e32 v109, v2
	v_mov_b32_e32 v110, v2
	v_mov_b32_e32 v111, v2
	v_mov_b32_e32 v112, v2
	v_mov_b32_e32 v113, v2
	v_mov_b32_e32 v122, v2
	v_mov_b32_e32 v123, v2
	v_mov_b32_e32 v124, v2
	v_mov_b32_e32 v125, v2
	v_mov_b32_e32 v126, v2
	v_mov_b32_e32 v127, v2
	v_mov_b32_e32 v128, v2
	v_mov_b32_e32 v129, v2
	.p2align 6

.LBB0_393:
	s_ashr_i32 s17, s16, 31
	s_lshl_b64 s[18:19], s[16:17], 19
	s_add_u32 s18, s26, s18
	s_addc_u32 s19, s27, s19
	s_and_b64 s[20:21], s[8:9], exec
	s_cselect_b32 s17, s19, s11
	s_cselect_b32 s42, s18, s10
	s_ashr_i32 s15, s14, 31
	s_lshl_b64 s[20:21], s[14:15], 19
	s_add_u32 s20, s28, s20
	s_addc_u32 s21, s29, s21
	s_and_b64 s[24:25], s[8:9], exec
	s_cselect_b32 s15, s21, s23
	s_cselect_b32 s43, s20, s22
	s_add_u32 s10, s10, 0x40080
	s_addc_u32 s11, s11, 0
	s_add_u32 s44, s22, 0x100
	v_mov_b32_e32 v2, 0
	s_addc_u32 s45, s23, 0
	s_mov_b32 s46, -2
	v_mov_b32_e32 v3, v2
	v_mov_b32_e32 v4, v2
	v_mov_b32_e32 v5, v2
	v_mov_b32_e32 v6, v2
	v_mov_b32_e32 v7, v2
	v_mov_b32_e32 v8, v2
	v_mov_b32_e32 v9, v2
	v_mov_b32_e32 v18, v2
	v_mov_b32_e32 v19, v2
	v_mov_b32_e32 v20, v2
	v_mov_b32_e32 v21, v2
	v_mov_b32_e32 v22, v2
	v_mov_b32_e32 v23, v2
	v_mov_b32_e32 v24, v2
	v_mov_b32_e32 v25, v2
	v_mov_b32_e32 v34, v2
	v_mov_b32_e32 v35, v2
	v_mov_b32_e32 v36, v2
	v_mov_b32_e32 v37, v2
	v_mov_b32_e32 v38, v2
	v_mov_b32_e32 v39, v2
	v_mov_b32_e32 v40, v2
	v_mov_b32_e32 v41, v2
	v_mov_b32_e32 v50, v2
	v_mov_b32_e32 v51, v2
	v_mov_b32_e32 v52, v2
	v_mov_b32_e32 v53, v2
	v_mov_b32_e32 v54, v2
	v_mov_b32_e32 v55, v2
	v_mov_b32_e32 v56, v2
	v_mov_b32_e32 v57, v2
	v_mov_b32_e32 v10, v2
	v_mov_b32_e32 v11, v2
	v_mov_b32_e32 v12, v2
	v_mov_b32_e32 v13, v2
	v_mov_b32_e32 v14, v2
	v_mov_b32_e32 v15, v2
	v_mov_b32_e32 v16, v2
	v_mov_b32_e32 v17, v2
	v_mov_b32_e32 v26, v2
	v_mov_b32_e32 v27, v2
	v_mov_b32_e32 v28, v2
	v_mov_b32_e32 v29, v2
	v_mov_b32_e32 v30, v2
	v_mov_b32_e32 v31, v2
	v_mov_b32_e32 v32, v2
	v_mov_b32_e32 v33, v2
	v_mov_b32_e32 v42, v2
	v_mov_b32_e32 v43, v2
	v_mov_b32_e32 v44, v2
	v_mov_b32_e32 v45, v2
	v_mov_b32_e32 v46, v2
	v_mov_b32_e32 v47, v2
	v_mov_b32_e32 v48, v2
	v_mov_b32_e32 v49, v2
	v_mov_b32_e32 v58, v2
	v_mov_b32_e32 v59, v2
	v_mov_b32_e32 v60, v2
	v_mov_b32_e32 v61, v2
	v_mov_b32_e32 v62, v2
	v_mov_b32_e32 v63, v2
	v_mov_b32_e32 v64, v2
	v_mov_b32_e32 v65, v2
	v_mov_b32_e32 v66, v2
	v_mov_b32_e32 v67, v2
	v_mov_b32_e32 v68, v2
	v_mov_b32_e32 v69, v2
	v_mov_b32_e32 v70, v2
	v_mov_b32_e32 v71, v2
	v_mov_b32_e32 v72, v2
	v_mov_b32_e32 v73, v2
	v_mov_b32_e32 v82, v2
	v_mov_b32_e32 v83, v2
	v_mov_b32_e32 v84, v2
	v_mov_b32_e32 v85, v2
	v_mov_b32_e32 v86, v2
	v_mov_b32_e32 v87, v2
	v_mov_b32_e32 v88, v2
	v_mov_b32_e32 v89, v2
	v_mov_b32_e32 v98, v2
	v_mov_b32_e32 v99, v2
	v_mov_b32_e32 v100, v2
	v_mov_b32_e32 v101, v2
	v_mov_b32_e32 v102, v2
	v_mov_b32_e32 v103, v2
	v_mov_b32_e32 v104, v2
	v_mov_b32_e32 v105, v2
	v_mov_b32_e32 v114, v2
	v_mov_b32_e32 v115, v2
	v_mov_b32_e32 v116, v2
	v_mov_b32_e32 v117, v2
	v_mov_b32_e32 v118, v2
	v_mov_b32_e32 v119, v2
	v_mov_b32_e32 v120, v2
	v_mov_b32_e32 v121, v2
	v_mov_b32_e32 v74, v2
	v_mov_b32_e32 v75, v2
	v_mov_b32_e32 v76, v2
	v_mov_b32_e32 v77, v2
	v_mov_b32_e32 v78, v2
	v_mov_b32_e32 v79, v2
	v_mov_b32_e32 v80, v2
	v_mov_b32_e32 v81, v2
	v_mov_b32_e32 v90, v2
	v_mov_b32_e32 v91, v2
	v_mov_b32_e32 v92, v2
	v_mov_b32_e32 v93, v2
	v_mov_b32_e32 v94, v2
	v_mov_b32_e32 v95, v2
	v_mov_b32_e32 v96, v2
	v_mov_b32_e32 v97, v2
	v_mov_b32_e32 v106, v2
	v_mov_b32_e32 v107, v2
	v_mov_b32_e32 v108, v2
	v_mov_b32_e32 v109, v2
	v_mov_b32_e32 v110, v2
	v_mov_b32_e32 v111, v2
	v_mov_b32_e32 v112, v2
	v_mov_b32_e32 v113, v2
	v_mov_b32_e32 v122, v2
	v_mov_b32_e32 v123, v2
	v_mov_b32_e32 v124, v2
	v_mov_b32_e32 v125, v2
	v_mov_b32_e32 v126, v2
	v_mov_b32_e32 v127, v2
	v_mov_b32_e32 v128, v2
	v_mov_b32_e32 v129, v2
	s_waitcnt vmcnt(0)
	.p2align 6

.LBB0_1401:
	s_add_u32 s44, s20, 0x100
	v_mov_b32_e32 v2, 0
	s_addc_u32 s45, s21, 0
	s_mov_b32 s46, -2
	v_mov_b32_e32 v3, v2
	v_mov_b32_e32 v4, v2
	v_mov_b32_e32 v5, v2
	v_mov_b32_e32 v6, v2
	v_mov_b32_e32 v7, v2
	v_mov_b32_e32 v8, v2
	v_mov_b32_e32 v9, v2
	v_mov_b32_e32 v18, v2
	v_mov_b32_e32 v19, v2
	v_mov_b32_e32 v20, v2
	v_mov_b32_e32 v21, v2
	v_mov_b32_e32 v22, v2
	v_mov_b32_e32 v23, v2
	v_mov_b32_e32 v24, v2
	v_mov_b32_e32 v25, v2
	v_mov_b32_e32 v34, v2
	v_mov_b32_e32 v35, v2
	v_mov_b32_e32 v36, v2
	v_mov_b32_e32 v37, v2
	v_mov_b32_e32 v38, v2
	v_mov_b32_e32 v39, v2
	v_mov_b32_e32 v40, v2
	v_mov_b32_e32 v41, v2
	v_mov_b32_e32 v50, v2
	v_mov_b32_e32 v51, v2
	v_mov_b32_e32 v52, v2
	v_mov_b32_e32 v53, v2
	v_mov_b32_e32 v54, v2
	v_mov_b32_e32 v55, v2
	v_mov_b32_e32 v56, v2
	v_mov_b32_e32 v57, v2
	v_mov_b32_e32 v10, v2
	v_mov_b32_e32 v11, v2
	v_mov_b32_e32 v12, v2
	v_mov_b32_e32 v13, v2
	v_mov_b32_e32 v14, v2
	v_mov_b32_e32 v15, v2
	v_mov_b32_e32 v16, v2
	v_mov_b32_e32 v17, v2
	v_mov_b32_e32 v26, v2
	v_mov_b32_e32 v27, v2
	v_mov_b32_e32 v28, v2
	v_mov_b32_e32 v29, v2
	v_mov_b32_e32 v30, v2
	v_mov_b32_e32 v31, v2
	v_mov_b32_e32 v32, v2
	v_mov_b32_e32 v33, v2
	v_mov_b32_e32 v42, v2
	v_mov_b32_e32 v43, v2
	v_mov_b32_e32 v44, v2
	v_mov_b32_e32 v45, v2
	v_mov_b32_e32 v46, v2
	v_mov_b32_e32 v47, v2
	v_mov_b32_e32 v48, v2
	v_mov_b32_e32 v49, v2
	v_mov_b32_e32 v58, v2
	v_mov_b32_e32 v59, v2
	v_mov_b32_e32 v60, v2
	v_mov_b32_e32 v61, v2
	v_mov_b32_e32 v62, v2
	v_mov_b32_e32 v63, v2
	v_mov_b32_e32 v64, v2
	v_mov_b32_e32 v65, v2
	v_mov_b32_e32 v66, v2
	v_mov_b32_e32 v67, v2
	v_mov_b32_e32 v68, v2
	v_mov_b32_e32 v69, v2
	v_mov_b32_e32 v70, v2
	v_mov_b32_e32 v71, v2
	v_mov_b32_e32 v72, v2
	v_mov_b32_e32 v73, v2
	v_mov_b32_e32 v82, v2
	v_mov_b32_e32 v83, v2
	v_mov_b32_e32 v84, v2
	v_mov_b32_e32 v85, v2
	v_mov_b32_e32 v86, v2
	v_mov_b32_e32 v87, v2
	v_mov_b32_e32 v88, v2
	v_mov_b32_e32 v89, v2
	v_mov_b32_e32 v98, v2
	v_mov_b32_e32 v99, v2
	v_mov_b32_e32 v100, v2
	v_mov_b32_e32 v101, v2
	v_mov_b32_e32 v102, v2
	v_mov_b32_e32 v103, v2
	v_mov_b32_e32 v104, v2
	v_mov_b32_e32 v105, v2
	v_mov_b32_e32 v114, v2
	v_mov_b32_e32 v115, v2
	v_mov_b32_e32 v116, v2
	v_mov_b32_e32 v117, v2
	v_mov_b32_e32 v118, v2
	v_mov_b32_e32 v119, v2
	v_mov_b32_e32 v120, v2
	v_mov_b32_e32 v121, v2
	v_mov_b32_e32 v74, v2
	v_mov_b32_e32 v75, v2
	v_mov_b32_e32 v76, v2
	v_mov_b32_e32 v77, v2
	v_mov_b32_e32 v78, v2
	v_mov_b32_e32 v79, v2
	v_mov_b32_e32 v80, v2
	v_mov_b32_e32 v81, v2
	v_mov_b32_e32 v90, v2
	v_mov_b32_e32 v91, v2
	v_mov_b32_e32 v92, v2
	v_mov_b32_e32 v93, v2
	v_mov_b32_e32 v94, v2
	v_mov_b32_e32 v95, v2
	v_mov_b32_e32 v96, v2
	v_mov_b32_e32 v97, v2
	v_mov_b32_e32 v106, v2
	v_mov_b32_e32 v107, v2
	v_mov_b32_e32 v108, v2
	v_mov_b32_e32 v109, v2
	v_mov_b32_e32 v110, v2
	v_mov_b32_e32 v111, v2
	v_mov_b32_e32 v112, v2
	v_mov_b32_e32 v113, v2
	v_mov_b32_e32 v122, v2
	v_mov_b32_e32 v123, v2
	v_mov_b32_e32 v124, v2
	v_mov_b32_e32 v125, v2
	v_mov_b32_e32 v126, v2
	v_mov_b32_e32 v127, v2
	v_mov_b32_e32 v128, v2
	v_mov_b32_e32 v129, v2
	.p2align 6

.LBB0_1425:
	s_add_u32 s44, s20, 0x100
	v_mov_b32_e32 v2, 0
	s_addc_u32 s45, s21, 0
	s_mov_b32 s46, -2
	v_mov_b32_e32 v3, v2
	v_mov_b32_e32 v4, v2
	v_mov_b32_e32 v5, v2
	v_mov_b32_e32 v6, v2
	v_mov_b32_e32 v7, v2
	v_mov_b32_e32 v8, v2
	v_mov_b32_e32 v9, v2
	v_mov_b32_e32 v18, v2
	v_mov_b32_e32 v19, v2
	v_mov_b32_e32 v20, v2
	v_mov_b32_e32 v21, v2
	v_mov_b32_e32 v22, v2
	v_mov_b32_e32 v23, v2
	v_mov_b32_e32 v24, v2
	v_mov_b32_e32 v25, v2
	v_mov_b32_e32 v34, v2
	v_mov_b32_e32 v35, v2
	v_mov_b32_e32 v36, v2
	v_mov_b32_e32 v37, v2
	v_mov_b32_e32 v38, v2
	v_mov_b32_e32 v39, v2
	v_mov_b32_e32 v40, v2
	v_mov_b32_e32 v41, v2
	v_mov_b32_e32 v50, v2
	v_mov_b32_e32 v51, v2
	v_mov_b32_e32 v52, v2
	v_mov_b32_e32 v53, v2
	v_mov_b32_e32 v54, v2
	v_mov_b32_e32 v55, v2
	v_mov_b32_e32 v56, v2
	v_mov_b32_e32 v57, v2
	v_mov_b32_e32 v10, v2
	v_mov_b32_e32 v11, v2
	v_mov_b32_e32 v12, v2
	v_mov_b32_e32 v13, v2
	v_mov_b32_e32 v14, v2
	v_mov_b32_e32 v15, v2
	v_mov_b32_e32 v16, v2
	v_mov_b32_e32 v17, v2
	v_mov_b32_e32 v26, v2
	v_mov_b32_e32 v27, v2
	v_mov_b32_e32 v28, v2
	v_mov_b32_e32 v29, v2
	v_mov_b32_e32 v30, v2
	v_mov_b32_e32 v31, v2
	v_mov_b32_e32 v32, v2
	v_mov_b32_e32 v33, v2
	v_mov_b32_e32 v42, v2
	v_mov_b32_e32 v43, v2
	v_mov_b32_e32 v44, v2
	v_mov_b32_e32 v45, v2
	v_mov_b32_e32 v46, v2
	v_mov_b32_e32 v47, v2
	v_mov_b32_e32 v48, v2
	v_mov_b32_e32 v49, v2
	v_mov_b32_e32 v58, v2
	v_mov_b32_e32 v59, v2
	v_mov_b32_e32 v60, v2
	v_mov_b32_e32 v61, v2
	v_mov_b32_e32 v62, v2
	v_mov_b32_e32 v63, v2
	v_mov_b32_e32 v64, v2
	v_mov_b32_e32 v65, v2
	v_mov_b32_e32 v66, v2
	v_mov_b32_e32 v67, v2
	v_mov_b32_e32 v68, v2
	v_mov_b32_e32 v69, v2
	v_mov_b32_e32 v70, v2
	v_mov_b32_e32 v71, v2
	v_mov_b32_e32 v72, v2
	v_mov_b32_e32 v73, v2
	v_mov_b32_e32 v82, v2
	v_mov_b32_e32 v83, v2
	v_mov_b32_e32 v84, v2
	v_mov_b32_e32 v85, v2
	v_mov_b32_e32 v86, v2
	v_mov_b32_e32 v87, v2
	v_mov_b32_e32 v88, v2
	v_mov_b32_e32 v89, v2
	v_mov_b32_e32 v98, v2
	v_mov_b32_e32 v99, v2
	v_mov_b32_e32 v100, v2
	v_mov_b32_e32 v101, v2
	v_mov_b32_e32 v102, v2
	v_mov_b32_e32 v103, v2
	v_mov_b32_e32 v104, v2
	v_mov_b32_e32 v105, v2
	v_mov_b32_e32 v114, v2
	v_mov_b32_e32 v115, v2
	v_mov_b32_e32 v116, v2
	v_mov_b32_e32 v117, v2
	v_mov_b32_e32 v118, v2
	v_mov_b32_e32 v119, v2
	v_mov_b32_e32 v120, v2
	v_mov_b32_e32 v121, v2
	v_mov_b32_e32 v74, v2
	v_mov_b32_e32 v75, v2
	v_mov_b32_e32 v76, v2
	v_mov_b32_e32 v77, v2
	v_mov_b32_e32 v78, v2
	v_mov_b32_e32 v79, v2
	v_mov_b32_e32 v80, v2
	v_mov_b32_e32 v81, v2
	v_mov_b32_e32 v90, v2
	v_mov_b32_e32 v91, v2
	v_mov_b32_e32 v92, v2
	v_mov_b32_e32 v93, v2
	v_mov_b32_e32 v94, v2
	v_mov_b32_e32 v95, v2
	v_mov_b32_e32 v96, v2
	v_mov_b32_e32 v97, v2
	v_mov_b32_e32 v106, v2
	v_mov_b32_e32 v107, v2
	v_mov_b32_e32 v108, v2
	v_mov_b32_e32 v109, v2
	v_mov_b32_e32 v110, v2
	v_mov_b32_e32 v111, v2
	v_mov_b32_e32 v112, v2
	v_mov_b32_e32 v113, v2
	v_mov_b32_e32 v122, v2
	v_mov_b32_e32 v123, v2
	v_mov_b32_e32 v124, v2
	v_mov_b32_e32 v125, v2
	v_mov_b32_e32 v126, v2
	v_mov_b32_e32 v127, v2
	v_mov_b32_e32 v128, v2
	v_mov_b32_e32 v129, v2
	s_waitcnt vmcnt(0)
	.p2align 6

.LBB0_1445:
	s_ashr_i32 s17, s16, 31
	s_lshl_b64 s[18:19], s[16:17], 17
	s_add_u32 s18, s42, s18
	s_addc_u32 s19, s43, s19
	s_and_b64 s[20:21], s[8:9], exec
	s_cselect_b32 s17, s19, s25
	s_cselect_b32 s56, s18, s24
	s_ashr_i32 s15, s14, 31
	s_lshl_b64 s[20:21], s[14:15], 17
	s_add_u32 s20, s44, s20
	s_addc_u32 s21, s45, s21
	s_and_b64 s[26:27], s[8:9], exec
	v_mov_b32_e32 v2, 0
	s_cselect_b32 s15, s21, s23
	s_cselect_b32 s57, s20, s22
	s_mov_b32 s30, 0
	s_mov_b64 s[26:27], -1
	s_mov_b64 s[28:29], 0
	v_mov_b32_e32 v3, v2
	v_mov_b32_e32 v4, v2
	v_mov_b32_e32 v5, v2
	v_mov_b32_e32 v6, v2
	v_mov_b32_e32 v7, v2
	v_mov_b32_e32 v8, v2
	v_mov_b32_e32 v9, v2
	v_mov_b32_e32 v18, v2
	v_mov_b32_e32 v19, v2
	v_mov_b32_e32 v20, v2
	v_mov_b32_e32 v21, v2
	v_mov_b32_e32 v22, v2
	v_mov_b32_e32 v23, v2
	v_mov_b32_e32 v24, v2
	v_mov_b32_e32 v25, v2
	v_mov_b32_e32 v34, v2
	v_mov_b32_e32 v35, v2
	v_mov_b32_e32 v36, v2
	v_mov_b32_e32 v37, v2
	v_mov_b32_e32 v38, v2
	v_mov_b32_e32 v39, v2
	v_mov_b32_e32 v40, v2
	v_mov_b32_e32 v41, v2
	v_mov_b32_e32 v50, v2
	v_mov_b32_e32 v51, v2
	v_mov_b32_e32 v52, v2
	v_mov_b32_e32 v53, v2
	v_mov_b32_e32 v54, v2
	v_mov_b32_e32 v55, v2
	v_mov_b32_e32 v56, v2
	v_mov_b32_e32 v57, v2
	v_mov_b32_e32 v10, v2
	v_mov_b32_e32 v11, v2
	v_mov_b32_e32 v12, v2
	v_mov_b32_e32 v13, v2
	v_mov_b32_e32 v14, v2
	v_mov_b32_e32 v15, v2
	v_mov_b32_e32 v16, v2
	v_mov_b32_e32 v17, v2
	v_mov_b32_e32 v26, v2
	v_mov_b32_e32 v27, v2
	v_mov_b32_e32 v28, v2
	v_mov_b32_e32 v29, v2
	v_mov_b32_e32 v30, v2
	v_mov_b32_e32 v31, v2
	v_mov_b32_e32 v32, v2
	v_mov_b32_e32 v33, v2
	v_mov_b32_e32 v42, v2
	v_mov_b32_e32 v43, v2
	v_mov_b32_e32 v44, v2
	v_mov_b32_e32 v45, v2
	v_mov_b32_e32 v46, v2
	v_mov_b32_e32 v47, v2
	v_mov_b32_e32 v48, v2
	v_mov_b32_e32 v49, v2
	v_mov_b32_e32 v58, v2
	v_mov_b32_e32 v59, v2
	v_mov_b32_e32 v60, v2
	v_mov_b32_e32 v61, v2
	v_mov_b32_e32 v62, v2
	v_mov_b32_e32 v63, v2
	v_mov_b32_e32 v64, v2
	v_mov_b32_e32 v65, v2
	v_mov_b32_e32 v66, v2
	v_mov_b32_e32 v67, v2
	v_mov_b32_e32 v68, v2
	v_mov_b32_e32 v69, v2
	v_mov_b32_e32 v70, v2
	v_mov_b32_e32 v71, v2
	v_mov_b32_e32 v72, v2
	v_mov_b32_e32 v73, v2
	v_mov_b32_e32 v82, v2
	v_mov_b32_e32 v83, v2
	v_mov_b32_e32 v84, v2
	v_mov_b32_e32 v85, v2
	v_mov_b32_e32 v86, v2
	v_mov_b32_e32 v87, v2
	v_mov_b32_e32 v88, v2
	v_mov_b32_e32 v89, v2
	v_mov_b32_e32 v98, v2
	v_mov_b32_e32 v99, v2
	v_mov_b32_e32 v100, v2
	v_mov_b32_e32 v101, v2
	v_mov_b32_e32 v102, v2
	v_mov_b32_e32 v103, v2
	v_mov_b32_e32 v104, v2
	v_mov_b32_e32 v105, v2
	v_mov_b32_e32 v114, v2
	v_mov_b32_e32 v115, v2
	v_mov_b32_e32 v116, v2
	v_mov_b32_e32 v117, v2
	v_mov_b32_e32 v118, v2
	v_mov_b32_e32 v119, v2
	v_mov_b32_e32 v120, v2
	v_mov_b32_e32 v121, v2
	v_mov_b32_e32 v74, v2
	v_mov_b32_e32 v75, v2
	v_mov_b32_e32 v76, v2
	v_mov_b32_e32 v77, v2
	v_mov_b32_e32 v78, v2
	v_mov_b32_e32 v79, v2
	v_mov_b32_e32 v80, v2
	v_mov_b32_e32 v81, v2
	v_mov_b32_e32 v90, v2
	v_mov_b32_e32 v91, v2
	v_mov_b32_e32 v92, v2
	v_mov_b32_e32 v93, v2
	v_mov_b32_e32 v94, v2
	v_mov_b32_e32 v95, v2
	v_mov_b32_e32 v96, v2
	v_mov_b32_e32 v97, v2
	v_mov_b32_e32 v106, v2
	v_mov_b32_e32 v107, v2
	v_mov_b32_e32 v108, v2
	v_mov_b32_e32 v109, v2
	v_mov_b32_e32 v110, v2
	v_mov_b32_e32 v111, v2
	v_mov_b32_e32 v112, v2
	v_mov_b32_e32 v113, v2
	v_mov_b32_e32 v122, v2
	v_mov_b32_e32 v123, v2
	v_mov_b32_e32 v124, v2
	v_mov_b32_e32 v125, v2
	v_mov_b32_e32 v126, v2
	v_mov_b32_e32 v127, v2
	v_mov_b32_e32 v128, v2
	v_mov_b32_e32 v129, v2
	s_waitcnt vmcnt(0)
	.p2align 6

.LBB0_1517:
	s_ashr_i32 s19, s18, 31
	s_lshl_b64 s[20:21], s[18:19], 19
	s_add_u32 s20, s34, s20
	s_addc_u32 s21, s35, s21
	s_and_b64 s[22:23], s[10:11], exec
	s_cselect_b32 s19, s21, s25
	s_cselect_b32 s49, s20, s24
	s_ashr_i32 s17, s16, 31
	s_lshl_b64 s[22:23], s[16:17], 19
	s_add_u32 s22, s36, s22
	s_addc_u32 s23, s37, s23
	s_and_b64 s[28:29], s[10:11], exec
	s_cselect_b32 s17, s23, s27
	s_cselect_b32 s50, s22, s26
	s_add_u32 s51, s26, 0x100
	v_mov_b32_e32 v2, 0
	s_addc_u32 s52, s27, 0
	s_mov_b32 s53, -2
	s_waitcnt lgkmcnt(0)
	v_mov_b32_e32 v3, v2
	v_mov_b32_e32 v4, v2
	v_mov_b32_e32 v5, v2
	v_mov_b32_e32 v6, v2
	v_mov_b32_e32 v7, v2
	v_mov_b32_e32 v8, v2
	v_mov_b32_e32 v9, v2
	v_mov_b32_e32 v18, v2
	v_mov_b32_e32 v19, v2
	v_mov_b32_e32 v20, v2
	v_mov_b32_e32 v21, v2
	v_mov_b32_e32 v22, v2
	v_mov_b32_e32 v23, v2
	v_mov_b32_e32 v24, v2
	v_mov_b32_e32 v25, v2
	v_mov_b32_e32 v34, v2
	v_mov_b32_e32 v35, v2
	v_mov_b32_e32 v36, v2
	v_mov_b32_e32 v37, v2
	v_mov_b32_e32 v38, v2
	v_mov_b32_e32 v39, v2
	v_mov_b32_e32 v40, v2
	v_mov_b32_e32 v41, v2
	v_mov_b32_e32 v50, v2
	v_mov_b32_e32 v51, v2
	v_mov_b32_e32 v52, v2
	v_mov_b32_e32 v53, v2
	v_mov_b32_e32 v54, v2
	v_mov_b32_e32 v55, v2
	v_mov_b32_e32 v56, v2
	v_mov_b32_e32 v57, v2
	v_mov_b32_e32 v10, v2
	v_mov_b32_e32 v11, v2
	v_mov_b32_e32 v12, v2
	v_mov_b32_e32 v13, v2
	v_mov_b32_e32 v14, v2
	v_mov_b32_e32 v15, v2
	v_mov_b32_e32 v16, v2
	v_mov_b32_e32 v17, v2
	v_mov_b32_e32 v26, v2
	v_mov_b32_e32 v27, v2
	v_mov_b32_e32 v28, v2
	v_mov_b32_e32 v29, v2
	v_mov_b32_e32 v30, v2
	v_mov_b32_e32 v31, v2
	v_mov_b32_e32 v32, v2
	v_mov_b32_e32 v33, v2
	v_mov_b32_e32 v42, v2
	v_mov_b32_e32 v43, v2
	v_mov_b32_e32 v44, v2
	v_mov_b32_e32 v45, v2
	v_mov_b32_e32 v46, v2
	v_mov_b32_e32 v47, v2
	v_mov_b32_e32 v48, v2
	v_mov_b32_e32 v49, v2
	v_mov_b32_e32 v58, v2
	v_mov_b32_e32 v59, v2
	v_mov_b32_e32 v60, v2
	v_mov_b32_e32 v61, v2
	v_mov_b32_e32 v62, v2
	v_mov_b32_e32 v63, v2
	v_mov_b32_e32 v64, v2
	v_mov_b32_e32 v65, v2
	v_mov_b32_e32 v66, v2
	v_mov_b32_e32 v67, v2
	v_mov_b32_e32 v68, v2
	v_mov_b32_e32 v69, v2
	v_mov_b32_e32 v70, v2
	v_mov_b32_e32 v71, v2
	v_mov_b32_e32 v72, v2
	v_mov_b32_e32 v73, v2
	v_mov_b32_e32 v82, v2
	v_mov_b32_e32 v83, v2
	v_mov_b32_e32 v84, v2
	v_mov_b32_e32 v85, v2
	v_mov_b32_e32 v86, v2
	v_mov_b32_e32 v87, v2
	v_mov_b32_e32 v88, v2
	v_mov_b32_e32 v89, v2
	v_mov_b32_e32 v98, v2
	v_mov_b32_e32 v99, v2
	v_mov_b32_e32 v100, v2
	v_mov_b32_e32 v101, v2
	v_mov_b32_e32 v102, v2
	v_mov_b32_e32 v103, v2
	v_mov_b32_e32 v104, v2
	v_mov_b32_e32 v105, v2
	v_mov_b32_e32 v114, v2
	v_mov_b32_e32 v115, v2
	v_mov_b32_e32 v116, v2
	v_mov_b32_e32 v117, v2
	v_mov_b32_e32 v118, v2
	v_mov_b32_e32 v119, v2
	v_mov_b32_e32 v120, v2
	v_mov_b32_e32 v121, v2
	v_mov_b32_e32 v74, v2
	v_mov_b32_e32 v75, v2
	v_mov_b32_e32 v76, v2
	v_mov_b32_e32 v77, v2
	v_mov_b32_e32 v78, v2
	v_mov_b32_e32 v79, v2
	v_mov_b32_e32 v80, v2
	v_mov_b32_e32 v81, v2
	v_mov_b32_e32 v90, v2
	v_mov_b32_e32 v91, v2
	v_mov_b32_e32 v92, v2
	v_mov_b32_e32 v93, v2
	v_mov_b32_e32 v94, v2
	v_mov_b32_e32 v95, v2
	v_mov_b32_e32 v96, v2
	v_mov_b32_e32 v97, v2
	v_mov_b32_e32 v106, v2
	v_mov_b32_e32 v107, v2
	v_mov_b32_e32 v108, v2
	v_mov_b32_e32 v109, v2
	v_mov_b32_e32 v110, v2
	v_mov_b32_e32 v111, v2
	v_mov_b32_e32 v112, v2
	v_mov_b32_e32 v113, v2
	v_mov_b32_e32 v122, v2
	v_mov_b32_e32 v123, v2
	v_mov_b32_e32 v124, v2
	v_mov_b32_e32 v125, v2
	v_mov_b32_e32 v126, v2
	v_mov_b32_e32 v127, v2
	v_mov_b32_e32 v128, v2
	v_mov_b32_e32 v129, v2
	.p2align 6

.LBB0_1601:
	s_ashr_i32 s15, s14, 31
	s_lshl_b64 s[16:17], s[14:15], 19
	s_add_u32 s16, s26, s16
	s_addc_u32 s17, s27, s17
	s_and_b64 s[18:19], s[6:7], exec
	s_cselect_b32 s15, s17, s21
	s_cselect_b32 s42, s16, s20
	s_ashr_i32 s13, s12, 31
	s_lshl_b64 s[18:19], s[12:13], 19
	s_add_u32 s18, s28, s18
	s_addc_u32 s19, s29, s19
	s_and_b64 s[24:25], s[6:7], exec
	s_cselect_b32 s13, s19, s23
	s_cselect_b32 s43, s18, s22
	s_add_u32 s20, s20, 0x40080
	s_addc_u32 s21, s21, 0
	s_add_u32 s44, s22, 0x100
	v_mov_b32_e32 v2, 0
	s_addc_u32 s45, s23, 0
	s_mov_b32 s46, -2
	v_mov_b32_e32 v3, v2
	v_mov_b32_e32 v4, v2
	v_mov_b32_e32 v5, v2
	v_mov_b32_e32 v6, v2
	v_mov_b32_e32 v7, v2
	v_mov_b32_e32 v8, v2
	v_mov_b32_e32 v9, v2
	v_mov_b32_e32 v18, v2
	v_mov_b32_e32 v19, v2
	v_mov_b32_e32 v20, v2
	v_mov_b32_e32 v21, v2
	v_mov_b32_e32 v22, v2
	v_mov_b32_e32 v23, v2
	v_mov_b32_e32 v24, v2
	v_mov_b32_e32 v25, v2
	v_mov_b32_e32 v34, v2
	v_mov_b32_e32 v35, v2
	v_mov_b32_e32 v36, v2
	v_mov_b32_e32 v37, v2
	v_mov_b32_e32 v38, v2
	v_mov_b32_e32 v39, v2
	v_mov_b32_e32 v40, v2
	v_mov_b32_e32 v41, v2
	v_mov_b32_e32 v50, v2
	v_mov_b32_e32 v51, v2
	v_mov_b32_e32 v52, v2
	v_mov_b32_e32 v53, v2
	v_mov_b32_e32 v54, v2
	v_mov_b32_e32 v55, v2
	v_mov_b32_e32 v56, v2
	v_mov_b32_e32 v57, v2
	v_mov_b32_e32 v10, v2
	v_mov_b32_e32 v11, v2
	v_mov_b32_e32 v12, v2
	v_mov_b32_e32 v13, v2
	v_mov_b32_e32 v14, v2
	v_mov_b32_e32 v15, v2
	v_mov_b32_e32 v16, v2
	v_mov_b32_e32 v17, v2
	v_mov_b32_e32 v26, v2
	v_mov_b32_e32 v27, v2
	v_mov_b32_e32 v28, v2
	v_mov_b32_e32 v29, v2
	v_mov_b32_e32 v30, v2
	v_mov_b32_e32 v31, v2
	v_mov_b32_e32 v32, v2
	v_mov_b32_e32 v33, v2
	v_mov_b32_e32 v42, v2
	v_mov_b32_e32 v43, v2
	v_mov_b32_e32 v44, v2
	v_mov_b32_e32 v45, v2
	v_mov_b32_e32 v46, v2
	v_mov_b32_e32 v47, v2
	v_mov_b32_e32 v48, v2
	v_mov_b32_e32 v49, v2
	v_mov_b32_e32 v58, v2
	v_mov_b32_e32 v59, v2
	v_mov_b32_e32 v60, v2
	v_mov_b32_e32 v61, v2
	v_mov_b32_e32 v62, v2
	v_mov_b32_e32 v63, v2
	v_mov_b32_e32 v64, v2
	v_mov_b32_e32 v65, v2
	v_mov_b32_e32 v66, v2
	v_mov_b32_e32 v67, v2
	v_mov_b32_e32 v68, v2
	v_mov_b32_e32 v69, v2
	v_mov_b32_e32 v70, v2
	v_mov_b32_e32 v71, v2
	v_mov_b32_e32 v72, v2
	v_mov_b32_e32 v73, v2
	v_mov_b32_e32 v82, v2
	v_mov_b32_e32 v83, v2
	v_mov_b32_e32 v84, v2
	v_mov_b32_e32 v85, v2
	v_mov_b32_e32 v86, v2
	v_mov_b32_e32 v87, v2
	v_mov_b32_e32 v88, v2
	v_mov_b32_e32 v89, v2
	v_mov_b32_e32 v98, v2
	v_mov_b32_e32 v99, v2
	v_mov_b32_e32 v100, v2
	v_mov_b32_e32 v101, v2
	v_mov_b32_e32 v102, v2
	v_mov_b32_e32 v103, v2
	v_mov_b32_e32 v104, v2
	v_mov_b32_e32 v105, v2
	v_mov_b32_e32 v114, v2
	v_mov_b32_e32 v115, v2
	v_mov_b32_e32 v116, v2
	v_mov_b32_e32 v117, v2
	v_mov_b32_e32 v118, v2
	v_mov_b32_e32 v119, v2
	v_mov_b32_e32 v120, v2
	v_mov_b32_e32 v121, v2
	v_mov_b32_e32 v74, v2
	v_mov_b32_e32 v75, v2
	v_mov_b32_e32 v76, v2
	v_mov_b32_e32 v77, v2
	v_mov_b32_e32 v78, v2
	v_mov_b32_e32 v79, v2
	v_mov_b32_e32 v80, v2
	v_mov_b32_e32 v81, v2
	v_mov_b32_e32 v90, v2
	v_mov_b32_e32 v91, v2
	v_mov_b32_e32 v92, v2
	v_mov_b32_e32 v93, v2
	v_mov_b32_e32 v94, v2
	v_mov_b32_e32 v95, v2
	v_mov_b32_e32 v96, v2
	v_mov_b32_e32 v97, v2
	v_mov_b32_e32 v106, v2
	v_mov_b32_e32 v107, v2
	v_mov_b32_e32 v108, v2
	v_mov_b32_e32 v109, v2
	v_mov_b32_e32 v110, v2
	v_mov_b32_e32 v111, v2
	v_mov_b32_e32 v112, v2
	v_mov_b32_e32 v113, v2
	v_mov_b32_e32 v122, v2
	v_mov_b32_e32 v123, v2
	v_mov_b32_e32 v124, v2
	v_mov_b32_e32 v125, v2
	v_mov_b32_e32 v126, v2
	v_mov_b32_e32 v127, v2
	v_mov_b32_e32 v128, v2
	v_mov_b32_e32 v129, v2
	s_waitcnt vmcnt(0)
	.p2align 6
